# unit-loop headers: runtime signed division by the always-8 tile-group size replaced by a shift (27-instruction reciprocal idiom with VALU rcp + readfirstlane removed at 10 sites)
# speedup vs baseline: 1.0061x; 1.0061x over previous
.LBB7_353:
	s_add_i32 s22, s22, 1
	s_mul_i32 s0, s22, s27
	s_mul_hi_u32 s1, s22, s60
	s_add_i32 s1, s1, s0
	s_mul_i32 s0, s22, s60
	s_add_u32 s0, s0, s2
	s_addc_u32 s1, s1, s59
	v_mov_b64_e32 v[2:3], 0xb00
	v_cmp_lt_i64_e64 s[40:41], s[0:1], v[2:3]
	v_mov_b64_e32 v[2:3], 0xaff
	v_cmp_gt_i64_e32 vcc, s[0:1], v[2:3]
	s_cbranch_vccnz .LBB7_355
	s_ashr_i32 s1, s0, 31
	s_lshr_b32 s1, s1, 29
	s_add_i32 s1, s0, s1
	s_ashr_i32 s6, s1, 3
	s_and_b32 s1, s1, -8
	s_sub_i32 s0, s0, s1
	s_cmp_lt_i32 s0, 0
	s_cselect_b32 s1, s76, 0x160
	s_mul_i32 s0, s0, s1
	s_add_i32 s0, s0, s6
	s_mul_hi_i32 s1, s0, 0x2e8ba2e9
	s_lshr_b32 s6, s1, 31
	s_ashr_i32 s1, s1, 5
	s_add_i32 s1, s1, s6
	s_lshl_b32 s6, s1, 3
	s_sub_i32 s7, 0x80, s6
	s_min_i32 s7, s7, 8
	s_mulk_i32 s1, 0xb0
	s_sub_i32 s0, s0, s1
	s_abs_i32 s1, s0
	s_ashr_i32 s8, s0, 3
	s_mul_i32 s1, s8, s7
	s_sub_i32 s0, s0, s1
	s_add_i32 s12, s6, s0
	s_ashr_i32 s13, s12, 31
	s_ashr_i32 s9, s8, 31
	s_lshl_b64 s[14:15], s[12:13], 19
	s_lshl_b64 s[18:19], s[8:9], 19

.LBB7_431:
	s_ashr_i32 s16, s20, 3
	s_add_i32 s16, s37, s16
	s_ashr_i32 s17, s16, 31
	s_lshr_b32 s17, s17, 27
	s_add_i32 s17, s16, s17
	s_ashr_i32 s20, s17, 5
	s_lshl_b32 s20, s20, 3
	s_sub_i32 s29, 0x80, s20
	s_min_i32 s29, s29, 8
	s_andn2_b32 s17, s17, 31
	s_sub_i32 s16, s16, s17
	s_abs_i32 s17, s16
	s_ashr_i32 s57, s16, 3
	s_mul_i32 s17, s57, s29
	s_sub_i32 s16, s16, s17
	s_add_i32 s88, s20, s16
	s_mul_hi_i32 s49, s88, 0x160000
	s_mul_i32 s48, s88, 0x160000
	s_mul_hi_i32 s51, s57, 0x160000
	s_mul_i32 s50, s57, 0x160000

.LBB7_519:
	s_add_i32 s73, s73, 1
	s_mul_i32 s13, s73, s27
	s_mul_hi_u32 s15, s73, s60
	s_add_i32 s15, s15, s13
	s_mul_i32 s13, s73, s60
	s_add_u32 s44, s13, s2
	s_addc_u32 s45, s15, s59
	v_mov_b64_e32 v[2:3], 0x300
	v_cmp_lt_i64_e64 s[40:41], s[44:45], v[2:3]
	v_mov_b64_e32 v[2:3], 0x2ff
	v_cmp_gt_i64_e32 vcc, s[44:45], v[2:3]
	s_cbranch_vccnz .LBB7_521
	s_ashr_i32 s12, s44, 31
	s_lshr_b32 s12, s12, 29
	s_add_i32 s12, s44, s12
	s_ashr_i32 s13, s12, 3
	s_and_b32 s12, s12, -8
	s_sub_i32 s12, s44, s12
	s_cmp_lt_i32 s12, 0
	s_movk_i32 s14, 0x61
	s_cselect_b32 s14, s14, 0x60
	s_mul_i32 s12, s12, s14
	s_add_i32 s12, s12, s13
	s_mul_hi_i32 s13, s12, 0x2aaaaaab
	s_lshr_b32 s14, s13, 31
	s_ashr_i32 s13, s13, 3
	s_add_i32 s13, s13, s14
	s_lshl_b32 s14, s13, 3
	s_sub_i32 s15, 0x80, s14
	s_min_i32 s15, s15, 8
	s_mul_i32 s13, s13, 48
	s_sub_i32 s13, s12, s13
	s_abs_i32 s12, s13
	s_ashr_i32 s12, s13, 3
	s_mul_i32 s15, s12, s15
	s_sub_i32 s13, s13, s15
	s_add_i32 s14, s14, s13
	s_ashr_i32 s15, s14, 31
	s_ashr_i32 s13, s12, 31
	s_lshl_b64 s[18:19], s[14:15], 19
	s_lshl_b64 s[50:51], s[12:13], 19

.LBB7_882:
	s_add_i32 s50, s50, 1
	s_mul_i32 s14, s50, s27
	s_mul_hi_u32 s15, s50, s60
	s_add_i32 s15, s15, s14
	s_mul_i32 s14, s50, s60
	s_add_u32 s14, s14, s2
	s_addc_u32 s15, s15, s59
	v_mov_b64_e32 v[2:3], 0xc0
	v_cmp_gt_i64_e32 vcc, s[14:15], v[168:169]
	v_cmp_lt_i64_e64 s[40:41], s[14:15], v[2:3]
	s_cbranch_vccnz .LBB7_884
	s_ashr_i32 s8, s14, 31
	s_lshr_b32 s8, s8, 29
	s_add_i32 s8, s14, s8
	s_ashr_i32 s9, s8, 3
	s_and_b32 s8, s8, -8
	s_sub_i32 s8, s14, s8
	s_cmp_lt_i32 s8, 0
	s_cselect_b32 s12, 25, 24
	s_mul_i32 s8, s8, s12
	s_add_i32 s8, s8, s9
	s_ashr_i32 s9, s8, 31
	s_lshr_b32 s9, s9, 28
	s_add_i32 s9, s8, s9
	s_ashr_i32 s12, s9, 4
	s_lshl_b32 s12, s12, 3
	s_sub_i32 s13, 0x60, s12
	s_min_i32 s13, s13, 8
	s_and_b32 s9, s9, -16
	s_sub_i32 s8, s8, s9
	s_abs_i32 s9, s8
	s_ashr_i32 s51, s8, 3
	s_mul_i32 s9, s51, s13
	s_sub_i32 s8, s8, s9
	s_add_i32 s53, s12, s8
	s_ashr_i32 s14, s53, 31
	s_lshr_b32 s14, s14, 30
	s_add_i32 s14, s53, s14
	s_lshl_b32 s8, s51, 2
	s_ashr_i32 s14, s14, 2
	s_add_i32 s52, s8, 6
	s_mul_i32 s12, s51, 0x50000
	s_mul_hi_i32 s15, s14, 0xa0000
	s_mul_i32 s14, s14, 0xa0000
	s_mul_hi_i32 s13, s51, 0x50000
	s_add_u32 s12, s14, s12
	s_mul_hi_i32 s9, s53, 0x50000
	s_mul_i32 s8, s53, 0x50000
	s_addc_u32 s13, s15, s13

.LBB7_960:
	s_ashr_i32 s12, s14, 3
	s_add_i32 s12, s18, s12
	s_ashr_i32 s13, s12, 31
	s_lshr_b32 s13, s13, 28
	s_add_i32 s13, s12, s13
	s_ashr_i32 s14, s13, 4
	s_lshl_b32 s14, s14, 3
	s_sub_i32 s15, 0x80, s14
	s_min_i32 s15, s15, 8
	s_and_b32 s13, s13, -16
	s_sub_i32 s12, s12, s13
	s_abs_i32 s13, s12
	s_ashr_i32 s54, s12, 3
	s_mul_i32 s13, s54, s15
	s_sub_i32 s12, s12, s13
	s_add_i32 s55, s14, s12
	s_mul_hi_i32 s13, s55, 0x30000
	s_mul_i32 s12, s55, 0x30000
	s_mul_hi_i32 s15, s54, 0x30000
	s_mul_i32 s14, s54, 0x30000

.LBB7_1101:
	s_ashr_i32 s12, s18, 3
	s_add_i32 s12, s20, s12
	s_ashr_i32 s13, s12, 31
	s_lshr_b32 s13, s13, 27
	s_add_i32 s13, s12, s13
	s_ashr_i32 s18, s13, 5
	s_lshl_b32 s20, s18, 3
	s_sub_i32 s18, 0x80, s20
	s_min_i32 s19, s18, 8
	s_andn2_b32 s13, s13, 31
	s_sub_i32 s12, s12, s13
	s_abs_i32 s13, s12
	s_ashr_i32 s18, s12, 3
	s_mul_i32 s13, s18, s19
	s_sub_i32 s12, s12, s13
	s_add_i32 s48, s20, s12
	s_ashr_i32 s19, s18, 31
	s_ashr_i32 s49, s48, 31
	s_lshl_b64 s[50:51], s[48:49], 19
	s_lshl_b64 s[52:53], s[18:19], 19

.LBB7_1193:
	s_ashr_i32 s12, s14, 3
	s_add_i32 s12, s18, s12
	s_ashr_i32 s13, s12, 31
	s_lshr_b32 s13, s13, 27
	s_add_i32 s13, s12, s13
	s_ashr_i32 s14, s13, 5
	s_lshl_b32 s14, s14, 3
	s_sub_i32 s15, 0x80, s14
	s_min_i32 s15, s15, 8
	s_andn2_b32 s13, s13, 31
	s_sub_i32 s19, s12, s13
	s_abs_i32 s12, s19
	s_ashr_i32 s12, s19, 3
	s_mul_i32 s15, s12, s15
	s_sub_i32 s15, s19, s15
	s_add_i32 s14, s14, s15
	s_ashr_i32 s13, s12, 31
	s_ashr_i32 s15, s14, 31
	s_lshl_b64 s[18:19], s[14:15], 19
	s_lshl_b64 s[44:45], s[12:13], 19

.LBB7_1216:
	s_ashr_i32 s10, s10, 3
	s_add_i32 s10, s15, s10
	s_ashr_i32 s12, s10, 31
	s_lshr_b32 s12, s12, 27
	s_add_i32 s12, s10, s12
	s_ashr_i32 s13, s12, 5
	s_lshl_b32 s14, s13, 3
	s_sub_i32 s13, 0x80, s14
	s_min_i32 s13, s13, 8
	s_andn2_b32 s12, s12, 31
	s_sub_i32 s10, s10, s12
	s_abs_i32 s12, s10
	s_ashr_i32 s12, s10, 3
	s_mul_i32 s15, s12, s13
	s_sub_i32 s10, s10, s15
	s_add_i32 s14, s14, s10
	s_ashr_i32 s13, s12, 31
	s_ashr_i32 s15, s14, 31
	s_lshl_b64 s[18:19], s[14:15], 19
	s_lshl_b64 s[28:29], s[12:13], 9
	s_add_u32 s18, s18, s28
	s_addc_u32 s19, s19, s29
	s_lshr_b32 s10, s15, 29
	s_add_i32 s10, s14, s10
	s_ashr_i32 s38, s10, 3
	s_ashr_i32 s39, s38, 31
	s_lshl_b64 s[38:39], s[38:39], 19
	s_add_u32 s44, s38, s28
	s_addc_u32 s45, s39, s29

.LBB7_1271:
	s_ashr_i32 s12, s14, 3
	s_add_i32 s12, s16, s12
	s_ashr_i32 s13, s12, 31
	s_lshr_b32 s13, s13, 27
	s_add_i32 s13, s12, s13
	s_ashr_i32 s14, s13, 5
	s_lshl_b32 s14, s14, 3
	s_sub_i32 s15, 0x80, s14
	s_min_i32 s15, s15, 8
	s_andn2_b32 s13, s13, 31
	s_sub_i32 s17, s12, s13
	s_abs_i32 s12, s17
	s_ashr_i32 s12, s17, 3
	s_mul_i32 s15, s12, s15
	s_sub_i32 s15, s17, s15
	s_add_i32 s14, s14, s15
	s_ashr_i32 s13, s12, 31
	s_ashr_i32 s15, s14, 31
	s_lshl_b64 s[16:17], s[14:15], 19
	s_lshl_b64 s[18:19], s[12:13], 9
	s_add_u32 s16, s16, s18
	s_addc_u32 s17, s17, s19
	s_lshl_b64 s[18:19], s[12:13], 21
	s_lshr_b32 s13, s15, 29
	s_add_i32 s13, s14, s13
	s_ashr_i32 s42, s13, 3
	s_ashr_i32 s43, s42, 31
	s_lshl_b64 s[42:43], s[42:43], 9
	s_add_u32 s18, s42, s18
	s_addc_u32 s19, s43, s19

.LBB7_1348:
	s_ashr_i32 s16, s18, 3
	s_add_i32 s16, s20, s16
	s_ashr_i32 s17, s16, 31
	s_lshr_b32 s17, s17, 27
	s_add_i32 s17, s16, s17
	s_ashr_i32 s18, s17, 5
	s_lshl_b32 s20, s18, 3
	s_sub_i32 s18, 0x80, s20
	s_min_i32 s19, s18, 8
	s_andn2_b32 s17, s17, 31
	s_sub_i32 s16, s16, s17
	s_abs_i32 s17, s16
	s_ashr_i32 s18, s16, 3
	s_mul_i32 s17, s18, s19
	s_sub_i32 s16, s16, s17
	s_add_i32 s48, s20, s16
	s_ashr_i32 s19, s18, 31
	s_ashr_i32 s49, s48, 31
	s_lshl_b64 s[50:51], s[48:49], 19
	s_lshl_b64 s[52:53], s[18:19], 19
